# attention loop: K/V fragment LDS reads issued up front with counted waits; attn_finish gain loads prefetched
# baseline (speedup 1.0000x reference)
.LBB0_983:
	ds_read_b128 v[194:197], v155 offset:24576
	ds_read_b128 v[198:201], v155 offset:26624
	ds_read_b128 v[202:205], v155 offset:28672
	ds_read_b128 v[206:209], v155 offset:30720
	ds_read_b128 v[210:213], v155 offset:25600
	ds_read_b128 v[214:217], v155 offset:27648
	ds_read_b128 v[218:221], v155 offset:29696
	ds_read_b128 v[222:225], v155 offset:31744
	v_fmamk_f32 v80, v80, 0x3e38aa3b, v149
	v_exp_f32_e32 v97, v80
	v_fmamk_f32 v80, v81, 0x3e38aa3b, v149
	v_exp_f32_e32 v110, v80
	v_fmamk_f32 v80, v82, 0x3e38aa3b, v149
	v_exp_f32_e32 v111, v80
	v_fmamk_f32 v80, v83, 0x3e38aa3b, v149
	v_exp_f32_e32 v148, v80
	v_fmamk_f32 v80, v84, 0x3e38aa3b, v149
	v_exp_f32_e32 v156, v80
	v_fmamk_f32 v80, v85, 0x3e38aa3b, v149
	v_exp_f32_e32 v157, v80
	v_fmamk_f32 v84, v86, 0x3e38aa3b, v149
	v_exp_f32_e32 v158, v84
	v_fmamk_f32 v84, v87, 0x3e38aa3b, v149
	v_exp_f32_e32 v159, v84
	v_cvt_pk_bf16_f32 v84, v97, v110
	v_cvt_pk_bf16_f32 v85, v111, v148
	v_cvt_pk_bf16_f32 v86, v156, v157
	v_cvt_pk_bf16_f32 v87, v158, v159
	v_fmamk_f32 v88, v88, 0x3e38aa3b, v149
	v_exp_f32_e32 v160, v88
	s_waitcnt lgkmcnt(7)
	v_mfma_f32_32x32x16_bf16 v[48:63], v[194:197], v[84:87], v[48:63]
	v_fmamk_f32 v163, v91, 0x3e38aa3b, v149
	v_fmamk_f32 v92, v92, 0x3e38aa3b, v149
	v_fmamk_f32 v93, v93, 0x3e38aa3b, v149
	v_fmamk_f32 v94, v94, 0x3e38aa3b, v149
	v_exp_f32_e32 v163, v163
	s_waitcnt lgkmcnt(6)
	v_mfma_f32_32x32x16_bf16 v[32:47], v[198:201], v[84:87], v[32:47]
	v_fmamk_f32 v80, v89, 0x3e38aa3b, v149
	v_exp_f32_e32 v161, v80
	v_fmamk_f32 v80, v90, 0x3e38aa3b, v149
	v_exp_f32_e32 v162, v80
	v_fmac_f32_e32 v149, 0x3e38aa3b, v95
	v_exp_f32_e32 v92, v92
	s_waitcnt lgkmcnt(5)
	v_mfma_f32_32x32x16_bf16 v[16:31], v[202:205], v[84:87], v[16:31]
	v_exp_f32_e32 v93, v93
	s_add_i32 s10, s10, 0x8000
	s_add_i32 s4, s4, 8
	s_add_i32 s11, s11, 1
	s_cmp_eq_u32 s10, 0x158000
	v_lshl_add_u64 v[146:147], v[146:147], 0, s[28:29]
	s_waitcnt lgkmcnt(4)
	v_mfma_f32_32x32x16_bf16 v[0:15], v[206:209], v[84:87], v[0:15]
	v_add_f32_e32 v86, 0, v97
	v_add_f32_e32 v86, v110, v86
	v_add_f32_e32 v86, v111, v86
	v_add_f32_e32 v86, v148, v86
	v_exp_f32_e32 v84, v94
	v_exp_f32_e32 v85, v149
	v_add_f32_e32 v86, v156, v86
	v_add_f32_e32 v86, v157, v86
	v_add_f32_e32 v86, v158, v86
	v_add_f32_e32 v86, v159, v86
	v_cvt_pk_bf16_f32 v80, v160, v161
	v_cvt_pk_bf16_f32 v81, v162, v163
	v_cvt_pk_bf16_f32 v82, v92, v93
	v_cvt_pk_bf16_f32 v83, v84, v85
	v_add_f32_e32 v86, v160, v86
	v_add_f32_e32 v86, v161, v86
	s_waitcnt lgkmcnt(0)
	v_mfma_f32_32x32x16_bf16 v[48:63], v[210:213], v[80:83], v[48:63]
	v_add_f32_e32 v86, v162, v86
	v_add_f32_e32 v86, v163, v86
	v_add_f32_e32 v86, v92, v86
	v_add_f32_e32 v86, v93, v86
	v_add_f32_e32 v84, v84, v86
	v_add_f32_e32 v84, v85, v84
	v_add_f32_e32 v148, v96, v84
	v_mfma_f32_32x32x16_bf16 v[32:47], v[214:217], v[80:83], v[32:47]
	v_mfma_f32_32x32x16_bf16 v[16:31], v[218:221], v[80:83], v[16:31]
	v_mfma_f32_32x32x16_bf16 v[0:15], v[222:225], v[80:83], v[0:15]
	s_cbranch_scc1 .LBB0_997

.LBB0_991:
	s_add_i32 s8, s10, 0xfffe8000
	s_and_b32 s8, s8, 0x18000
	s_add_i32 s8, s8, 0
	v_add_u32_e32 v100, s8, v128
	v_add_u32_e32 v155, s8, v152
	ds_read_b128 v[80:83], v100 offset:16384
	ds_read_b128 v[96:99], v100 offset:17408
	ds_read_b128 v[186:189], v100 offset:18432
	ds_read_b128 v[190:193], v100 offset:19456
	ds_read_b128 v[194:197], v155 offset:8192
	ds_read_b128 v[198:201], v155 offset:10240
	ds_read_b128 v[202:205], v155 offset:12288
	ds_read_b128 v[206:209], v155 offset:14336
	ds_read_b128 v[210:213], v155 offset:9216
	ds_read_b128 v[214:217], v155 offset:11264
	ds_read_b128 v[218:221], v155 offset:13312
	ds_read_b128 v[222:225], v155 offset:15360
	v_max_f32_e32 v101, v65, v65
	v_max_f32_e32 v102, v64, v64
	v_max_f32_e32 v101, v102, v101
	s_waitcnt lgkmcnt(11)
	v_mfma_f32_32x32x16_bf16 v[80:95], v[80:83], v[112:115], 0
	v_max3_f32 v104, v101, v66, v67
	s_waitcnt lgkmcnt(10)
	v_mfma_f32_32x32x16_bf16 v[80:95], v[96:99], v[116:119], v[80:95]
	s_waitcnt lgkmcnt(9)
	v_mfma_f32_32x32x16_bf16 v[80:95], v[186:189], v[120:123], v[80:95]
	v_max3_f32 v96, v104, v68, v69
	v_max3_f32 v96, v96, v70, v71
	v_max3_f32 v96, v96, v72, v73
	v_max3_f32 v96, v96, v74, v75
	v_max3_f32 v96, v96, v76, v77
	v_max3_f32 v96, v96, v78, v79
	v_mov_b32_e32 v97, v96
	s_waitcnt lgkmcnt(8)
	v_mfma_f32_32x32x16_bf16 v[80:95], v[190:193], v[124:127], v[80:95]
	s_nop 0
	v_permlane32_swap_b32_e32 v96, v97
	v_max_f32_e32 v97, v97, v97
	v_max_f32_e32 v96, v96, v96
	v_max_f32_e32 v96, v96, v97
	v_add_f32_e32 v97, 0x42317218, v140
	v_cmp_gt_f32_e32 vcc, v96, v97
	s_cbranch_vccz .LBB0_993
	v_max_f32_e32 v96, v96, v96
	v_max_f32_e32 v97, v140, v140
	v_max_f32_e32 v97, v97, v96
	v_sub_f32_e32 v96, v140, v97
	v_mul_f32_e32 v96, 0x3e38aa3b, v96
	v_exp_f32_e32 v96, v96
	v_mov_b32_e32 v140, v97
	v_pk_mul_f32 v[62:63], v[62:63], v[96:97] op_sel_hi:[1,0]
	v_pk_mul_f32 v[60:61], v[60:61], v[96:97] op_sel_hi:[1,0]
	v_pk_mul_f32 v[58:59], v[58:59], v[96:97] op_sel_hi:[1,0]
	v_pk_mul_f32 v[56:57], v[56:57], v[96:97] op_sel_hi:[1,0]
	v_pk_mul_f32 v[54:55], v[54:55], v[96:97] op_sel_hi:[1,0]
	v_pk_mul_f32 v[52:53], v[52:53], v[96:97] op_sel_hi:[1,0]
	v_pk_mul_f32 v[50:51], v[50:51], v[96:97] op_sel_hi:[1,0]
	v_pk_mul_f32 v[48:49], v[48:49], v[96:97] op_sel_hi:[1,0]
	v_pk_mul_f32 v[46:47], v[46:47], v[96:97] op_sel_hi:[1,0]
	v_pk_mul_f32 v[44:45], v[44:45], v[96:97] op_sel_hi:[1,0]
	v_pk_mul_f32 v[42:43], v[42:43], v[96:97] op_sel_hi:[1,0]
	v_pk_mul_f32 v[40:41], v[40:41], v[96:97] op_sel_hi:[1,0]
	v_pk_mul_f32 v[38:39], v[38:39], v[96:97] op_sel_hi:[1,0]
	v_pk_mul_f32 v[36:37], v[36:37], v[96:97] op_sel_hi:[1,0]
	v_pk_mul_f32 v[34:35], v[34:35], v[96:97] op_sel_hi:[1,0]
	v_pk_mul_f32 v[32:33], v[32:33], v[96:97] op_sel_hi:[1,0]
	v_pk_mul_f32 v[30:31], v[30:31], v[96:97] op_sel_hi:[1,0]
	v_pk_mul_f32 v[28:29], v[28:29], v[96:97] op_sel_hi:[1,0]
	v_pk_mul_f32 v[26:27], v[26:27], v[96:97] op_sel_hi:[1,0]
	v_pk_mul_f32 v[24:25], v[24:25], v[96:97] op_sel_hi:[1,0]
	v_pk_mul_f32 v[22:23], v[22:23], v[96:97] op_sel_hi:[1,0]
	v_pk_mul_f32 v[20:21], v[20:21], v[96:97] op_sel_hi:[1,0]
	v_pk_mul_f32 v[18:19], v[18:19], v[96:97] op_sel_hi:[1,0]
	v_pk_mul_f32 v[16:17], v[16:17], v[96:97] op_sel_hi:[1,0]
	v_pk_mul_f32 v[14:15], v[14:15], v[96:97] op_sel_hi:[1,0]
	v_pk_mul_f32 v[12:13], v[12:13], v[96:97] op_sel_hi:[1,0]
	v_pk_mul_f32 v[10:11], v[10:11], v[96:97] op_sel_hi:[1,0]
	v_pk_mul_f32 v[8:9], v[8:9], v[96:97] op_sel_hi:[1,0]
	v_pk_mul_f32 v[6:7], v[6:7], v[96:97] op_sel_hi:[1,0]
	v_pk_mul_f32 v[4:5], v[4:5], v[96:97] op_sel_hi:[1,0]
	v_pk_mul_f32 v[2:3], v[2:3], v[96:97] op_sel_hi:[1,0]
	v_pk_mul_f32 v[0:1], v[0:1], v[96:97] op_sel_hi:[1,0]
	v_mul_f32_e32 v148, v148, v96
.LBB0_993:
	v_mul_f32_e32 v149, 0xbe38aa3b, v140
	v_fmamk_f32 v64, v64, 0x3e38aa3b, v149
	v_exp_f32_e32 v96, v64
	v_fmamk_f32 v64, v65, 0x3e38aa3b, v149
	v_exp_f32_e32 v97, v64
	v_fmamk_f32 v64, v66, 0x3e38aa3b, v149
	v_exp_f32_e32 v98, v64
	v_fmamk_f32 v64, v67, 0x3e38aa3b, v149
	v_exp_f32_e32 v99, v64
	v_fmamk_f32 v64, v68, 0x3e38aa3b, v149
	v_exp_f32_e32 v100, v64
	v_fmamk_f32 v64, v69, 0x3e38aa3b, v149
	v_exp_f32_e32 v101, v64
	v_fmamk_f32 v68, v70, 0x3e38aa3b, v149
	v_exp_f32_e32 v102, v68
	v_fmamk_f32 v68, v71, 0x3e38aa3b, v149
	v_exp_f32_e32 v103, v68
	v_cvt_pk_bf16_f32 v68, v96, v97
	v_cvt_pk_bf16_f32 v69, v98, v99
	v_cvt_pk_bf16_f32 v70, v100, v101
	v_cvt_pk_bf16_f32 v71, v102, v103
	v_fmamk_f32 v72, v72, 0x3e38aa3b, v149
	v_exp_f32_e32 v104, v72
	s_waitcnt lgkmcnt(7)
	v_mfma_f32_32x32x16_bf16 v[48:63], v[194:197], v[68:71], v[48:63]
	v_fmamk_f32 v107, v75, 0x3e38aa3b, v149
	v_fmamk_f32 v76, v76, 0x3e38aa3b, v149
	v_exp_f32_e32 v107, v107
	s_andn2_b64 vcc, exec, s[6:7]
	s_waitcnt lgkmcnt(6)
	v_mfma_f32_32x32x16_bf16 v[32:47], v[198:201], v[68:71], v[32:47]
	v_fmamk_f32 v64, v73, 0x3e38aa3b, v149
	v_exp_f32_e32 v105, v64
	v_fmamk_f32 v64, v74, 0x3e38aa3b, v149
	v_exp_f32_e32 v106, v64
	v_cvt_pk_bf16_f32 v182, v104, v105
	s_waitcnt lgkmcnt(5)
	v_mfma_f32_32x32x16_bf16 v[16:31], v[202:205], v[68:71], v[16:31]
	v_exp_f32_e32 v108, v76
	v_fmamk_f32 v76, v77, 0x3e38aa3b, v149
	v_exp_f32_e32 v109, v76
	v_fmamk_f32 v76, v78, 0x3e38aa3b, v149
	v_exp_f32_e32 v110, v76
	v_cvt_pk_bf16_f32 v183, v106, v107
	v_cvt_pk_bf16_f32 v184, v108, v109
	s_waitcnt lgkmcnt(4)
	v_mfma_f32_32x32x16_bf16 v[0:15], v[206:209], v[68:71], v[0:15]
	v_fmamk_f32 v64, v79, 0x3e38aa3b, v149
	v_exp_f32_e32 v111, v64
	s_nop 0
	v_cvt_pk_bf16_f32 v185, v110, v111
	s_nop 1
	s_waitcnt lgkmcnt(0)
	v_mfma_f32_32x32x16_bf16 v[48:63], v[210:213], v[182:185], v[48:63]
	v_mfma_f32_32x32x16_bf16 v[32:47], v[214:217], v[182:185], v[32:47]
	v_mfma_f32_32x32x16_bf16 v[16:31], v[218:221], v[182:185], v[16:31]
	v_mov_b64_e32 v[64:65], v[96:97]
	v_mov_b64_e32 v[66:67], v[98:99]
	v_mov_b64_e32 v[68:69], v[100:101]
	v_mov_b64_e32 v[70:71], v[102:103]
	v_mov_b64_e32 v[72:73], v[104:105]
	v_mov_b64_e32 v[74:75], v[106:107]
	v_mov_b64_e32 v[76:77], v[108:109]
	v_mfma_f32_32x32x16_bf16 v[0:15], v[222:225], v[182:185], v[0:15]
	v_mov_b64_e32 v[78:79], v[110:111]
	s_cbranch_vccnz .LBB0_995
	s_add_i32 s6, s10, 0xffff0000
	s_and_b32 s6, s6, 0x18000
	v_add_u32_e32 v160, s6, v154
	ds_read_b128 v[64:67], v160
	ds_read_b128 v[156:159], v160 offset:1024
	s_waitcnt lgkmcnt(0)
	v_mfma_f32_32x32x16_bf16 v[64:79], v[64:67], v[112:115], 0
	v_mfma_f32_32x32x16_bf16 v[64:79], v[156:159], v[116:119], v[64:79]
	ds_read_b128 v[156:159], v160 offset:2048
	ds_read_b128 v[160:163], v160 offset:3072
	s_waitcnt lgkmcnt(0)
	v_mfma_f32_32x32x16_bf16 v[64:79], v[156:159], v[120:123], v[64:79]
	v_mfma_f32_32x32x16_bf16 v[64:79], v[160:163], v[124:127], v[64:79]

.LBB0_999:
	s_waitcnt lgkmcnt(0)
	s_barrier
	s_andn2_b64 vcc, exec, s[6:7]
	s_cbranch_vccnz .LBB0_981
	ds_read2st64_b32 v[70:71], v64 offset1:1
	ds_read2st64_b32 v[72:73], v64 offset0:2 offset1:3
	ds_read2st64_b32 v[74:75], v64 offset0:4 offset1:5
	ds_read2st64_b32 v[76:77], v64 offset0:6 offset1:7
	ds_read2st64_b32 v[78:79], v64 offset0:8 offset1:9
	ds_read2st64_b32 v[80:81], v64 offset0:10 offset1:11
	ds_read2st64_b32 v[82:83], v64 offset0:12 offset1:13
	ds_read2st64_b32 v[84:85], v64 offset0:14 offset1:15
	ds_read2st64_b32 v[86:87], v64 offset0:16 offset1:17
	ds_read2st64_b32 v[88:89], v64 offset0:18 offset1:19
	ds_read2st64_b32 v[90:91], v64 offset0:20 offset1:21
	ds_read2st64_b32 v[92:93], v64 offset0:22 offset1:23
	ds_read2st64_b32 v[94:95], v64 offset0:24 offset1:25
	ds_read2st64_b32 v[96:97], v64 offset0:26 offset1:27
	ds_read2st64_b32 v[98:99], v64 offset0:28 offset1:29
	ds_read2st64_b32 v[100:101], v64 offset0:30 offset1:31
	ds_read2st64_b32 v[102:103], v64 offset0:32 offset1:33
	ds_read2st64_b32 v[104:105], v64 offset0:34 offset1:35
	ds_read2st64_b32 v[106:107], v64 offset0:36 offset1:37
	ds_read2st64_b32 v[108:109], v64 offset0:38 offset1:39
	ds_read2st64_b32 v[110:111], v64 offset0:40 offset1:41
	ds_read2st64_b32 v[112:113], v64 offset0:42 offset1:43
	ds_read2st64_b32 v[114:115], v64 offset0:44 offset1:45
	ds_read2st64_b32 v[116:117], v64 offset0:46 offset1:47
	ds_read2st64_b32 v[118:119], v64 offset0:56 offset1:57
	ds_read2st64_b32 v[120:121], v64 offset0:58 offset1:59
	ds_read2st64_b32 v[66:67], v64 offset0:60 offset1:61
	ds_read2st64_b32 v[122:123], v64 offset0:62 offset1:63
	ds_read2st64_b32 v[124:125], v64 offset0:48 offset1:49
	ds_read2st64_b32 v[126:127], v64 offset0:50 offset1:51
	ds_read2st64_b32 v[144:145], v64 offset0:52 offset1:53
	ds_read2st64_b32 v[146:147], v64 offset0:54 offset1:55
	s_load_dwordx2 s[6:7], s[20:21], 0x68
	s_waitcnt lgkmcnt(0)
	v_pk_fma_f32 v[64:65], v[12:13], v[68:69], v[66:67] op_sel_hi:[1,0,1] neg_lo:[0,0,1] neg_hi:[0,0,1]
	v_pk_fma_f32 v[66:67], v[14:15], v[68:69], v[122:123] op_sel_hi:[1,0,1] neg_lo:[0,0,1] neg_hi:[0,0,1]
	v_lshlrev_b32_e32 v69, 2, v132
	v_pk_fma_f32 v[70:71], v[48:49], v[68:69], v[70:71] op_sel_hi:[1,0,1] neg_lo:[0,0,1] neg_hi:[0,0,1]
	v_pk_fma_f32 v[50:51], v[50:51], v[68:69], v[72:73] op_sel_hi:[1,0,1] neg_lo:[0,0,1] neg_hi:[0,0,1]
	v_pk_mul_f32 v[154:155], v[70:71], v[70:71]
	global_load_dwordx4 v[12:15], v69, s[6:7]
	global_load_dwordx4 v[186:189], v69, s[6:7] offset:32
	global_load_dwordx4 v[190:193], v69, s[6:7] offset:64
	global_load_dwordx4 v[194:197], v69, s[6:7] offset:96
	global_load_dwordx4 v[198:201], v69, s[6:7] offset:128
	global_load_dwordx4 v[202:205], v69, s[6:7] offset:160
	global_load_dwordx4 v[206:209], v69, s[6:7] offset:192
	global_load_dwordx4 v[210:213], v69, s[6:7] offset:224
	global_load_dwordx4 v[214:217], v69, s[6:7] offset:256
	global_load_dwordx4 v[218:221], v69, s[6:7] offset:288
	global_load_dwordx4 v[222:225], v69, s[6:7] offset:320
	global_load_dwordx4 v[226:229], v69, s[6:7] offset:352
	v_pk_mul_f32 v[72:73], v[50:51], v[50:51]
	v_pk_fma_f32 v[54:55], v[54:55], v[68:69], v[76:77] op_sel_hi:[1,0,1] neg_lo:[0,0,1] neg_hi:[0,0,1]
	v_pk_fma_f32 v[74:75], v[52:53], v[68:69], v[74:75] op_sel_hi:[1,0,1] neg_lo:[0,0,1] neg_hi:[0,0,1]
	v_pk_fma_f32 v[58:59], v[58:59], v[68:69], v[80:81] op_sel_hi:[1,0,1] neg_lo:[0,0,1] neg_hi:[0,0,1]
	v_pk_fma_f32 v[56:57], v[56:57], v[68:69], v[78:79] op_sel_hi:[1,0,1] neg_lo:[0,0,1] neg_hi:[0,0,1]
	v_pk_fma_f32 v[62:63], v[62:63], v[68:69], v[84:85] op_sel_hi:[1,0,1] neg_lo:[0,0,1] neg_hi:[0,0,1]
	v_pk_fma_f32 v[60:61], v[60:61], v[68:69], v[82:83] op_sel_hi:[1,0,1] neg_lo:[0,0,1] neg_hi:[0,0,1]
	v_pk_fma_f32 v[52:53], v[34:35], v[68:69], v[88:89] op_sel_hi:[1,0,1] neg_lo:[0,0,1] neg_hi:[0,0,1]
	v_pk_fma_f32 v[86:87], v[32:33], v[68:69], v[86:87] op_sel_hi:[1,0,1] neg_lo:[0,0,1] neg_hi:[0,0,1]
	v_pk_fma_f32 v[48:49], v[38:39], v[68:69], v[92:93] op_sel_hi:[1,0,1] neg_lo:[0,0,1] neg_hi:[0,0,1]
	v_pk_fma_f32 v[90:91], v[36:37], v[68:69], v[90:91] op_sel_hi:[1,0,1] neg_lo:[0,0,1] neg_hi:[0,0,1]
	v_pk_fma_f32 v[38:39], v[42:43], v[68:69], v[96:97] op_sel_hi:[1,0,1] neg_lo:[0,0,1] neg_hi:[0,0,1]
	v_pk_fma_f32 v[94:95], v[40:41], v[68:69], v[94:95] op_sel_hi:[1,0,1] neg_lo:[0,0,1] neg_hi:[0,0,1]
	v_pk_fma_f32 v[34:35], v[46:47], v[68:69], v[100:101] op_sel_hi:[1,0,1] neg_lo:[0,0,1] neg_hi:[0,0,1]
	v_pk_fma_f32 v[44:45], v[44:45], v[68:69], v[98:99] op_sel_hi:[1,0,1] neg_lo:[0,0,1] neg_hi:[0,0,1]
	v_pk_fma_f32 v[32:33], v[18:19], v[68:69], v[104:105] op_sel_hi:[1,0,1] neg_lo:[0,0,1] neg_hi:[0,0,1]
	v_pk_fma_f32 v[42:43], v[16:17], v[68:69], v[102:103] op_sel_hi:[1,0,1] neg_lo:[0,0,1] neg_hi:[0,0,1]
	v_pk_fma_f32 v[22:23], v[22:23], v[68:69], v[108:109] op_sel_hi:[1,0,1] neg_lo:[0,0,1] neg_hi:[0,0,1]
	v_pk_fma_f32 v[40:41], v[20:21], v[68:69], v[106:107] op_sel_hi:[1,0,1] neg_lo:[0,0,1] neg_hi:[0,0,1]
	v_pk_fma_f32 v[20:21], v[26:27], v[68:69], v[112:113] op_sel_hi:[1,0,1] neg_lo:[0,0,1] neg_hi:[0,0,1]
	v_pk_fma_f32 v[36:37], v[24:25], v[68:69], v[110:111] op_sel_hi:[1,0,1] neg_lo:[0,0,1] neg_hi:[0,0,1]
	v_pk_fma_f32 v[18:19], v[30:31], v[68:69], v[116:117] op_sel_hi:[1,0,1] neg_lo:[0,0,1] neg_hi:[0,0,1]
	v_pk_fma_f32 v[26:27], v[28:29], v[68:69], v[114:115] op_sel_hi:[1,0,1] neg_lo:[0,0,1] neg_hi:[0,0,1]
	v_pk_fma_f32 v[16:17], v[2:3], v[68:69], v[126:127] op_sel_hi:[1,0,1] neg_lo:[0,0,1] neg_hi:[0,0,1]
	v_pk_fma_f32 v[24:25], v[0:1], v[68:69], v[124:125] op_sel_hi:[1,0,1] neg_lo:[0,0,1] neg_hi:[0,0,1]
	v_pk_fma_f32 v[2:3], v[6:7], v[68:69], v[146:147] op_sel_hi:[1,0,1] neg_lo:[0,0,1] neg_hi:[0,0,1]
	v_pk_fma_f32 v[6:7], v[4:5], v[68:69], v[144:145] op_sel_hi:[1,0,1] neg_lo:[0,0,1] neg_hi:[0,0,1]
	v_pk_fma_f32 v[0:1], v[10:11], v[68:69], v[120:121] op_sel_hi:[1,0,1] neg_lo:[0,0,1] neg_hi:[0,0,1]
	v_pk_fma_f32 v[4:5], v[8:9], v[68:69], v[118:119] op_sel_hi:[1,0,1] neg_lo:[0,0,1] neg_hi:[0,0,1]
	v_add_f32_e32 v68, v154, v155
	v_add_f32_e32 v68, v72, v68
	v_pk_mul_f32 v[156:157], v[74:75], v[74:75]
	v_add_f32_e32 v68, v73, v68
	v_add_f32_e32 v68, v156, v68
	v_pk_mul_f32 v[76:77], v[54:55], v[54:55]
	v_add_f32_e32 v68, v157, v68
	v_add_f32_e32 v68, v76, v68
	v_pk_mul_f32 v[78:79], v[56:57], v[56:57]
	v_add_f32_e32 v68, v77, v68
	v_add_f32_e32 v68, v78, v68
	v_pk_mul_f32 v[80:81], v[58:59], v[58:59]
	v_add_f32_e32 v68, v79, v68
	v_add_f32_e32 v68, v80, v68
	v_pk_mul_f32 v[82:83], v[60:61], v[60:61]
	v_add_f32_e32 v68, v81, v68
	v_add_f32_e32 v68, v82, v68
	v_pk_mul_f32 v[84:85], v[62:63], v[62:63]
	v_add_f32_e32 v68, v83, v68
	v_add_f32_e32 v68, v84, v68
	v_pk_mul_f32 v[158:159], v[86:87], v[86:87]
	v_add_f32_e32 v68, v85, v68
	v_add_f32_e32 v68, v158, v68
	v_pk_mul_f32 v[88:89], v[52:53], v[52:53]
	v_add_f32_e32 v68, v159, v68
	v_add_f32_e32 v68, v88, v68
	v_pk_mul_f32 v[160:161], v[90:91], v[90:91]
	v_add_f32_e32 v68, v89, v68
	v_add_f32_e32 v68, v160, v68
	v_pk_mul_f32 v[92:93], v[48:49], v[48:49]
	v_add_f32_e32 v68, v161, v68
	v_add_f32_e32 v68, v92, v68
	v_pk_mul_f32 v[162:163], v[94:95], v[94:95]
	v_add_f32_e32 v68, v93, v68
	v_add_f32_e32 v68, v162, v68
	v_pk_mul_f32 v[96:97], v[38:39], v[38:39]
	v_add_f32_e32 v68, v163, v68
	v_add_f32_e32 v68, v96, v68
	v_pk_mul_f32 v[98:99], v[44:45], v[44:45]
	v_add_f32_e32 v68, v97, v68
	v_add_f32_e32 v68, v98, v68
	v_pk_mul_f32 v[46:47], v[34:35], v[34:35]
	v_add_f32_e32 v68, v99, v68
	v_add_f32_e32 v46, v46, v68
	v_pk_mul_f32 v[102:103], v[42:43], v[42:43]
	v_add_f32_e32 v46, v47, v46
	v_add_f32_e32 v46, v102, v46
	v_pk_mul_f32 v[100:101], v[32:33], v[32:33]
	v_add_f32_e32 v46, v103, v46
	v_add_f32_e32 v46, v100, v46
	v_pk_mul_f32 v[106:107], v[40:41], v[40:41]
	v_add_f32_e32 v46, v101, v46
	v_add_f32_e32 v46, v106, v46
	v_pk_mul_f32 v[104:105], v[22:23], v[22:23]
	v_add_f32_e32 v46, v107, v46
	v_add_f32_e32 v46, v104, v46
	v_pk_mul_f32 v[110:111], v[36:37], v[36:37]
	v_add_f32_e32 v46, v105, v46
	v_add_f32_e32 v46, v110, v46
	v_pk_mul_f32 v[108:109], v[20:21], v[20:21]
	v_add_f32_e32 v46, v111, v46
	v_add_f32_e32 v46, v108, v46
	v_pk_mul_f32 v[28:29], v[26:27], v[26:27]
	v_add_f32_e32 v46, v109, v46
	v_add_f32_e32 v28, v28, v46
	v_pk_mul_f32 v[30:31], v[18:19], v[18:19]
	v_add_f32_e32 v28, v29, v28
	v_add_f32_e32 v28, v30, v28
	v_pk_mul_f32 v[114:115], v[24:25], v[24:25]
	v_add_f32_e32 v28, v31, v28
	v_add_f32_e32 v28, v114, v28
	v_pk_mul_f32 v[112:113], v[16:17], v[16:17]
	v_add_f32_e32 v28, v115, v28
	v_add_f32_e32 v28, v112, v28
	v_pk_mul_f32 v[124:125], v[6:7], v[6:7]
	v_add_f32_e32 v28, v113, v28
	v_add_f32_e32 v28, v124, v28
	v_pk_mul_f32 v[116:117], v[2:3], v[2:3]
	v_add_f32_e32 v28, v125, v28
	v_add_f32_e32 v28, v116, v28
	v_pk_mul_f32 v[8:9], v[4:5], v[4:5]
	v_add_f32_e32 v28, v117, v28
	v_add_f32_e32 v8, v8, v28
	v_pk_mul_f32 v[10:11], v[0:1], v[0:1]
	v_add_f32_e32 v8, v9, v8
	v_add_f32_e32 v8, v10, v8
	v_pk_mul_f32 v[148:149], v[64:65], v[64:65]
	v_add_f32_e32 v8, v11, v8
	v_add_f32_e32 v8, v148, v8
	v_pk_mul_f32 v[122:123], v[66:67], v[66:67]
	v_add_f32_e32 v8, v149, v8
	v_add_f32_e32 v8, v122, v8
	v_add_f32_e32 v10, v123, v8
	ds_bpermute_b32 v11, v171, v10
	v_lshlrev_b64 v[8:9], 11, v[142:143]
	v_lshl_add_u64 v[8:9], s[24:25], 0, v[8:9]
	s_lshl_b32 s4, s57, 1
	v_lshl_add_u64 v[8:9], v[8:9], 0, s[4:5]
	s_waitcnt lgkmcnt(0)
	v_add_f32_e32 v10, v10, v11
	v_fmamk_f32 v10, v10, 0x3c000000, v153
	v_mul_f32_e32 v11, 0x4b800000, v10
	v_cmp_gt_f32_e32 vcc, s56, v10
	v_lshlrev_b32_e32 v128, 1, v132
	v_lshl_add_u64 v[28:29], v[8:9], 0, v[128:129]
	v_cndmask_b32_e32 v10, v10, v11, vcc
	v_rsq_f32_e32 v10, v10
	s_nop 0
	v_mul_f32_e32 v8, 0x45800000, v10
	v_cndmask_b32_e32 v8, v10, v8, vcc
	v_mul_f32_e32 v30, 0x3f4ccccd, v8
	v_pk_mul_f32 v[8:9], v[70:71], v[30:31] op_sel_hi:[1,0]
	v_pk_mul_f32 v[10:11], v[50:51], v[30:31] op_sel_hi:[1,0]
	s_waitcnt vmcnt(11)
	v_pk_mul_f32 v[8:9], v[12:13], v[8:9]
	v_pk_mul_f32 v[10:11], v[14:15], v[10:11]
	v_cvt_pk_bf16_f32 v8, v8, v9
	v_cvt_pk_bf16_f32 v9, v10, v11
	global_store_dwordx2 v[28:29], v[8:9], off
	v_pk_mul_f32 v[12:13], v[74:75], v[30:31] op_sel_hi:[1,0]
	v_pk_mul_f32 v[14:15], v[58:59], v[30:31] op_sel_hi:[1,0]
	v_pk_mul_f32 v[6:7], v[6:7], v[30:31] op_sel_hi:[1,0]
	v_pk_mul_f32 v[2:3], v[2:3], v[30:31] op_sel_hi:[1,0]
	v_pk_mul_f32 v[0:1], v[0:1], v[30:31] op_sel_hi:[1,0]
	s_waitcnt vmcnt(11)
	v_mov_b64_e32 v[8:9], v[186:187]
	v_mov_b64_e32 v[10:11], v[188:189]
	v_pk_mul_f32 v[8:9], v[8:9], v[12:13]
	v_pk_mul_f32 v[12:13], v[54:55], v[30:31] op_sel_hi:[1,0]
	v_cvt_pk_bf16_f32 v8, v8, v9
	v_pk_mul_f32 v[10:11], v[10:11], v[12:13]
	v_pk_mul_f32 v[12:13], v[56:57], v[30:31] op_sel_hi:[1,0]
	v_cvt_pk_bf16_f32 v9, v10, v11
	global_store_dwordx2 v[28:29], v[8:9], off offset:16
	s_waitcnt vmcnt(11)
	v_mov_b64_e32 v[8:9], v[190:191]
	v_mov_b64_e32 v[10:11], v[192:193]
	v_pk_mul_f32 v[8:9], v[8:9], v[12:13]
	v_pk_mul_f32 v[10:11], v[10:11], v[14:15]
	v_cvt_pk_bf16_f32 v8, v8, v9
	v_cvt_pk_bf16_f32 v9, v10, v11
	global_store_dwordx2 v[28:29], v[8:9], off offset:32
	v_pk_mul_f32 v[12:13], v[60:61], v[30:31] op_sel_hi:[1,0]
	v_pk_mul_f32 v[14:15], v[62:63], v[30:31] op_sel_hi:[1,0]
	s_waitcnt vmcnt(11)
	v_mov_b64_e32 v[8:9], v[194:195]
	v_mov_b64_e32 v[10:11], v[196:197]
	v_pk_mul_f32 v[8:9], v[8:9], v[12:13]
	v_pk_mul_f32 v[10:11], v[10:11], v[14:15]
	v_cvt_pk_bf16_f32 v8, v8, v9
	v_cvt_pk_bf16_f32 v9, v10, v11
	global_store_dwordx2 v[28:29], v[8:9], off offset:48
	v_pk_mul_f32 v[12:13], v[86:87], v[30:31] op_sel_hi:[1,0]
	v_pk_mul_f32 v[14:15], v[52:53], v[30:31] op_sel_hi:[1,0]
	s_waitcnt vmcnt(11)
	v_mov_b64_e32 v[8:9], v[198:199]
	v_mov_b64_e32 v[10:11], v[200:201]
	v_pk_mul_f32 v[8:9], v[8:9], v[12:13]
	v_pk_mul_f32 v[10:11], v[10:11], v[14:15]
	v_cvt_pk_bf16_f32 v8, v8, v9
	v_cvt_pk_bf16_f32 v9, v10, v11
	global_store_dwordx2 v[28:29], v[8:9], off offset:64
	global_load_dwordx4 v[186:189], v69, s[6:7] offset:384
	global_load_dwordx4 v[190:193], v69, s[6:7] offset:416
	global_load_dwordx4 v[194:197], v69, s[6:7] offset:448
	global_load_dwordx4 v[198:201], v69, s[6:7] offset:480
	v_pk_mul_f32 v[12:13], v[90:91], v[30:31] op_sel_hi:[1,0]
	v_pk_mul_f32 v[14:15], v[48:49], v[30:31] op_sel_hi:[1,0]
	s_waitcnt vmcnt(15)
	v_mov_b64_e32 v[8:9], v[202:203]
	v_mov_b64_e32 v[10:11], v[204:205]
	v_pk_mul_f32 v[8:9], v[8:9], v[12:13]
	v_pk_mul_f32 v[10:11], v[10:11], v[14:15]
	v_cvt_pk_bf16_f32 v8, v8, v9
	v_cvt_pk_bf16_f32 v9, v10, v11
	global_store_dwordx2 v[28:29], v[8:9], off offset:80
	v_pk_mul_f32 v[12:13], v[94:95], v[30:31] op_sel_hi:[1,0]
	v_pk_mul_f32 v[14:15], v[38:39], v[30:31] op_sel_hi:[1,0]
	s_waitcnt vmcnt(15)
	v_mov_b64_e32 v[8:9], v[206:207]
	v_mov_b64_e32 v[10:11], v[208:209]
	v_pk_mul_f32 v[8:9], v[12:13], v[8:9]
	v_pk_mul_f32 v[10:11], v[14:15], v[10:11]
	v_cvt_pk_bf16_f32 v8, v8, v9
	v_cvt_pk_bf16_f32 v9, v10, v11
	global_store_dwordx2 v[28:29], v[8:9], off offset:96
	v_pk_mul_f32 v[12:13], v[44:45], v[30:31] op_sel_hi:[1,0]
	v_pk_mul_f32 v[14:15], v[34:35], v[30:31] op_sel_hi:[1,0]
	s_waitcnt vmcnt(15)
	v_mov_b64_e32 v[8:9], v[210:211]
	v_mov_b64_e32 v[10:11], v[212:213]
	v_pk_mul_f32 v[8:9], v[12:13], v[8:9]
	v_pk_mul_f32 v[10:11], v[14:15], v[10:11]
	v_cvt_pk_bf16_f32 v8, v8, v9
	v_cvt_pk_bf16_f32 v9, v10, v11
	global_store_dwordx2 v[28:29], v[8:9], off offset:112
	v_pk_mul_f32 v[12:13], v[42:43], v[30:31] op_sel_hi:[1,0]
	v_pk_mul_f32 v[14:15], v[32:33], v[30:31] op_sel_hi:[1,0]
	s_waitcnt vmcnt(15)
	v_mov_b64_e32 v[8:9], v[214:215]
	v_mov_b64_e32 v[10:11], v[216:217]
	v_pk_mul_f32 v[8:9], v[12:13], v[8:9]
	v_pk_mul_f32 v[10:11], v[14:15], v[10:11]
	v_cvt_pk_bf16_f32 v8, v8, v9
	v_cvt_pk_bf16_f32 v9, v10, v11
	global_store_dwordx2 v[28:29], v[8:9], off offset:128
	v_pk_mul_f32 v[12:13], v[40:41], v[30:31] op_sel_hi:[1,0]
	v_pk_mul_f32 v[14:15], v[22:23], v[30:31] op_sel_hi:[1,0]
	s_waitcnt vmcnt(15)
	v_mov_b64_e32 v[8:9], v[218:219]
	v_mov_b64_e32 v[10:11], v[220:221]
	v_pk_mul_f32 v[8:9], v[12:13], v[8:9]
	v_pk_mul_f32 v[10:11], v[14:15], v[10:11]
	v_cvt_pk_bf16_f32 v8, v8, v9
	v_cvt_pk_bf16_f32 v9, v10, v11
	global_store_dwordx2 v[28:29], v[8:9], off offset:144
	v_pk_mul_f32 v[12:13], v[36:37], v[30:31] op_sel_hi:[1,0]
	v_pk_mul_f32 v[14:15], v[20:21], v[30:31] op_sel_hi:[1,0]
	s_waitcnt vmcnt(15)
	v_mov_b64_e32 v[8:9], v[222:223]
	v_mov_b64_e32 v[10:11], v[224:225]
	v_pk_mul_f32 v[8:9], v[12:13], v[8:9]
	v_pk_mul_f32 v[10:11], v[14:15], v[10:11]
	v_cvt_pk_bf16_f32 v8, v8, v9
	v_cvt_pk_bf16_f32 v9, v10, v11
	global_store_dwordx2 v[28:29], v[8:9], off offset:160
	v_pk_mul_f32 v[12:13], v[26:27], v[30:31] op_sel_hi:[1,0]
	v_pk_mul_f32 v[14:15], v[18:19], v[30:31] op_sel_hi:[1,0]
	s_waitcnt vmcnt(15)
	v_mov_b64_e32 v[8:9], v[226:227]
	v_mov_b64_e32 v[10:11], v[228:229]
	v_pk_mul_f32 v[8:9], v[12:13], v[8:9]
	v_pk_mul_f32 v[10:11], v[14:15], v[10:11]
	v_cvt_pk_bf16_f32 v8, v8, v9
	v_cvt_pk_bf16_f32 v9, v10, v11
	global_store_dwordx2 v[28:29], v[8:9], off offset:176
	v_pk_mul_f32 v[12:13], v[24:25], v[30:31] op_sel_hi:[1,0]
	v_pk_mul_f32 v[14:15], v[16:17], v[30:31] op_sel_hi:[1,0]
	s_waitcnt vmcnt(10)
	v_mov_b64_e32 v[8:9], v[186:187]
	v_mov_b64_e32 v[10:11], v[188:189]
	v_pk_mul_f32 v[8:9], v[12:13], v[8:9]
	v_pk_mul_f32 v[10:11], v[14:15], v[10:11]
	v_cvt_pk_bf16_f32 v8, v8, v9
	v_cvt_pk_bf16_f32 v9, v10, v11
	global_store_dwordx2 v[28:29], v[8:9], off offset:192
	s_waitcnt vmcnt(10)
	v_mov_b64_e32 v[8:9], v[190:191]
	v_mov_b64_e32 v[10:11], v[192:193]
	v_pk_mul_f32 v[6:7], v[6:7], v[8:9]
	v_pk_mul_f32 v[2:3], v[2:3], v[10:11]
	v_cvt_pk_bf16_f32 v6, v6, v7
	v_cvt_pk_bf16_f32 v7, v2, v3
	global_store_dwordx2 v[28:29], v[6:7], off offset:208
	v_pk_mul_f32 v[2:3], v[4:5], v[30:31] op_sel_hi:[1,0]
	v_pk_mul_f32 v[4:5], v[64:65], v[30:31] op_sel_hi:[1,0]
	s_waitcnt vmcnt(10)
	v_mov_b64_e32 v[6:7], v[194:195]
	v_mov_b64_e32 v[8:9], v[196:197]
	v_pk_mul_f32 v[2:3], v[2:3], v[6:7]
	v_pk_mul_f32 v[0:1], v[0:1], v[8:9]
	v_cvt_pk_bf16_f32 v2, v2, v3
	v_cvt_pk_bf16_f32 v3, v0, v1
	global_store_dwordx2 v[28:29], v[2:3], off offset:224
	v_pk_mul_f32 v[6:7], v[66:67], v[30:31] op_sel_hi:[1,0]
	s_waitcnt vmcnt(10)
	v_mov_b64_e32 v[0:1], v[198:199]
	v_mov_b64_e32 v[2:3], v[200:201]
	v_pk_mul_f32 v[0:1], v[4:5], v[0:1]
	v_pk_mul_f32 v[2:3], v[6:7], v[2:3]
	v_cvt_pk_bf16_f32 v0, v0, v1
	v_cvt_pk_bf16_f32 v1, v2, v3
	global_store_dwordx2 v[28:29], v[0:1], off offset:240
	s_branch .LBB0_981
